# v20: P2 main GEMM k-loop stages k-tiles HBM->LDS directly (lockstep loop, no ping-pong)
# baseline (speedup 1.0000x reference)
;   __device__ __forceinline__ bool natural_group(int tile_row) const { return ((n0 + tile_row) >> 5) == 20; }
; template <int AMODE, int BN, class Epi>
; __device__ __forceinline__ void gemm_tile(const bf16_t* A, const int lda, const bf16_t* Bt, const int K, const int m0, const float* mu, char* lds, const Epi& epi) {
;   constexpr int WN = BN / 64, MI = WN, NBR = BN / 64, G_STAGE = (256 + BN) * G_LDT;
;   const int tid = threadIdx.x, lane = tid & 63, wid = tid >> 6, r32 = lane & 31, hi = lane >> 5;
;   const int wm = wid / WN, wn = wid % WN;
;   const int srow = tid >> 3, scc = (tid & 7) * 8;
;   int browi[NBR];
; #pragma unroll
;   for (int i = 0; i < NBR; ++i) browi[i] = 64 * i + ((Epi::PERM && !epi.natural_group(64 * i + srow)) ? ((srow & 32) + 16 * ((srow >> 2) & 1) + 4 * ((srow & 31) >> 3) + (srow & 3)) : srow);
;   f32x16 acc[MI][2];
; #pragma unroll
;   for (int i = 0; i < MI; ++i)
; #pragma unroll
;     for (int j = 0; j < 2; ++j)
; #pragma unroll
;       for (int r = 0; r < 16; ++r) acc[i][j][r] = 0.f;
;   bf16x8 ra[4], rb[NBR], rp[4], rn[4];
;   float ssq[4] = {0.f, 0.f, 0.f, 0.f};
;   int dprev[4], dnext[4];
;   if constexpr (AMODE == 1) {
;     const int t0 = m0 % TL;
; #pragma unroll
;     for (int i = 0; i < 4; ++i) { const int t = t0 + srow + 64 * i; dprev[i] = (t != 0 && t != T) ? 1 : 0; dnext[i] = (t != T - 1 && t != TL - 1) ? 1 : 0; }
;   }
;   auto gload = [&](int k0) {
; #pragma unroll
;     for (int i = 0; i < 4; ++i) {
;       const bf16_t* ap = A + (size_t)(m0 + srow + 64 * i) * lda + k0 + scc;
;       ra[i] = *(const bf16x8*)ap;
;       if constexpr (AMODE == 1) { rp[i] = *(const bf16x8*)(ap - dprev[i] * lda); rn[i] = *(const bf16x8*)(ap + dnext[i] * lda); }
;     }
; #pragma unroll
;     for (int i = 0; i < NBR; ++i) rb[i] = *(const bf16x8*)(Bt + (size_t)browi[i] * K + k0 + scc);
;   };
.LBB0_407:
	v_or_b32_e32 v0, s20, v161
	v_ashrrev_i32_e32 v1, 31, v0
	v_lshlrev_b64 v[48:49], 11, v[0:1]
	v_lshl_add_u64 v[2:3], s[16:17], 0, v[48:49]
	v_lshl_add_u64 v[52:53], v[48:49], 0, s[14:15]
	s_lshl_b32 s18, s48, 8
	v_lshl_add_u64 v[50:51], v[2:3], 0, v[170:171]
	v_lshl_add_u64 v[2:3], s[16:17], 0, v[52:53]
	s_and_b32 s21, s18, 0x300
	s_lshl_b32 s18, s4, 10
	v_lshl_add_u64 v[54:55], v[2:3], 0, v[170:171]
	v_or_b32_e32 v2, 0x80, v0
	v_add_u32_e32 v0, 0xc0, v0
	s_or_b32 s18, s21, s18
	v_ashrrev_i32_e32 v1, 31, v0
	s_ashr_i32 s19, s18, 31
	v_lshlrev_b64 v[60:61], 11, v[0:1]
	s_lshl_b64 s[18:19], s[18:19], 11
	v_lshl_add_u64 v[0:1], s[16:17], 0, v[60:61]
	v_lshl_add_u64 v[62:63], v[0:1], 0, v[170:171]
	v_lshl_add_u64 v[0:1], v[164:165], 0, s[18:19]
	v_lshl_add_u64 v[64:65], v[0:1], 0, v[170:171]
	v_add_co_u32_e32 v66, vcc, s34, v64
	v_ashrrev_i32_e32 v3, 31, v2
	s_nop 0
	v_addc_co_u32_e32 v67, vcc, 0, v65, vcc
	v_add_co_u32_e32 v68, vcc, s35, v64
	v_lshlrev_b64 v[56:57], 11, v[2:3]
	s_nop 0
	v_addc_co_u32_e32 v69, vcc, 0, v65, vcc
	v_lshl_add_u64 v[2:3], s[16:17], 0, v[56:57]
	v_add_co_u32_e32 v70, vcc, s43, v64
	v_lshl_add_u64 v[58:59], v[2:3], 0, v[170:171]
	s_nop 0
	v_addc_co_u32_e32 v71, vcc, 0, v65, vcc
	global_load_dwordx4 v[16:19], v[50:51], off
	global_load_dwordx4 v[128:131], v[50:51], off offset:128
	global_load_dwordx4 v[20:23], v[54:55], off
	global_load_dwordx4 v[24:27], v[58:59], off
	global_load_dwordx4 v[28:31], v[62:63], off
	global_load_dwordx4 v[32:35], v[64:65], off
	global_load_dwordx4 v[36:39], v[66:67], off
	global_load_dwordx4 v[40:43], v[68:69], off
	global_load_dwordx4 v[44:47], v[70:71], off
	global_load_dwordx4 v[132:135], v[54:55], off offset:128
	global_load_dwordx4 v[136:139], v[58:59], off offset:128
	global_load_dwordx4 v[140:143], v[62:63], off offset:128
	global_load_dwordx4 v[144:147], v[64:65], off offset:128
	global_load_dwordx4 v[148:151], v[66:67], off offset:128
	global_load_dwordx4 v[152:155], v[68:69], off offset:128
	global_load_dwordx4 v[156:159], v[70:71], off offset:128
	s_lshl_b32 s72, s20, 11
	s_add_u32 s66, s16, s72
	s_addc_u32 s67, s17, 0
	s_add_u32 s66, s66, 0x80
	s_addc_u32 s67, s67, 0
	v_mov_b32_e32 v0, 0
	s_mov_b32 s22, 0
	s_mov_b64 s[16:17], 0
	v_mov_b32_e32 v1, v0
	v_mov_b32_e32 v2, v0
	v_mov_b32_e32 v3, v0
	v_mov_b32_e32 v4, v0
	v_mov_b32_e32 v5, v0
	v_mov_b32_e32 v6, v0
	v_mov_b32_e32 v7, v0
	v_mov_b32_e32 v8, v0
	v_mov_b32_e32 v9, v0
	v_mov_b32_e32 v10, v0
	v_mov_b32_e32 v11, v0
	v_mov_b32_e32 v12, v0
	v_mov_b32_e32 v13, v0
	v_mov_b32_e32 v14, v0
	v_mov_b32_e32 v15, v0
	s_add_u32 s68, s86, s18
	s_addc_u32 s69, s87, s19
	s_add_u32 s68, s68, 0x3c540080
	s_addc_u32 s69, s69, 0
	v_readfirstlane_b32 s96, v182
	s_nop 0
	s_cmp_lt_u32 s96, 4
	s_cselect_b32 s72, s66, s68
	s_cselect_b32 s73, s67, s69
	s_lshl_b32 s92, s96, 6
	s_lshl_b32 s96, s96, 10
	v_and_b32_e32 v48, 63, v178
	v_add_u32_e32 v48, s92, v48
	s_nop 0
	v_mul_u32_u24_e32 v50, 0x1c72, v48
	v_lshrrev_b32_e32 v50, 16, v50
	v_mul_u32_u24_e32 v51, 9, v50
	v_sub_u32_e32 v51, v48, v51
	v_lshlrev_b32_e32 v52, 11, v50
	v_lshl_add_u32 v52, v51, 4, v52
	v_and_b32_e32 v53, 0xe3, v50
	v_bfe_u32 v54, v50, 2, 1
	v_lshl_or_b32 v53, v54, 4, v53
	v_bfe_u32 v54, v50, 3, 2
	v_lshl_or_b32 v53, v54, 2, v53
	v_lshlrev_b32_e32 v53, 11, v53
	v_lshl_add_u32 v53, v51, 4, v53
	v_cmp_lt_u32_e32 vcc, 0xff, v50
	v_cndmask_b32_e32 v52, v52, v53, vcc
	v_cmp_eq_u32_e32 vcc, 8, v51
	v_cndmask_b32_e64 v194, v52, 0, vcc
	v_add_u32_e32 v49, 0x200, v48
	v_mul_u32_u24_e32 v50, 0x1c72, v49
	v_lshrrev_b32_e32 v50, 16, v50
	v_mul_u32_u24_e32 v51, 9, v50
	v_sub_u32_e32 v51, v49, v51
	v_lshlrev_b32_e32 v52, 11, v50
	v_lshl_add_u32 v52, v51, 4, v52
	v_and_b32_e32 v53, 0xe3, v50
	v_bfe_u32 v54, v50, 2, 1
	v_lshl_or_b32 v53, v54, 4, v53
	v_bfe_u32 v54, v50, 3, 2
	v_lshl_or_b32 v53, v54, 2, v53
	v_lshlrev_b32_e32 v53, 11, v53
	v_lshl_add_u32 v53, v51, 4, v53
	v_cmp_lt_u32_e32 vcc, 0xff, v50
	v_cndmask_b32_e32 v52, v52, v53, vcc
	v_cmp_eq_u32_e32 vcc, 8, v51
	v_cndmask_b32_e64 v195, v52, 0, vcc
	v_add_u32_e32 v49, 0x400, v48
	v_mul_u32_u24_e32 v50, 0x1c72, v49
	v_lshrrev_b32_e32 v50, 16, v50
	v_mul_u32_u24_e32 v51, 9, v50
	v_sub_u32_e32 v51, v49, v51
	v_lshlrev_b32_e32 v52, 11, v50
	v_lshl_add_u32 v52, v51, 4, v52
	v_and_b32_e32 v53, 0xe3, v50
	v_bfe_u32 v54, v50, 2, 1
	v_lshl_or_b32 v53, v54, 4, v53
	v_bfe_u32 v54, v50, 3, 2
	v_lshl_or_b32 v53, v54, 2, v53
	v_lshlrev_b32_e32 v53, 11, v53
	v_lshl_add_u32 v53, v51, 4, v53
	v_cmp_lt_u32_e32 vcc, 0xff, v50
	v_cndmask_b32_e32 v52, v52, v53, vcc
	v_cmp_eq_u32_e32 vcc, 8, v51
	v_cndmask_b32_e64 v196, v52, 0, vcc
	v_add_u32_e32 v49, 0x600, v48
	v_mul_u32_u24_e32 v50, 0x1c72, v49
	v_lshrrev_b32_e32 v50, 16, v50
	v_mul_u32_u24_e32 v51, 9, v50
	v_sub_u32_e32 v51, v49, v51
	v_lshlrev_b32_e32 v52, 11, v50
	v_lshl_add_u32 v52, v51, 4, v52
	v_and_b32_e32 v53, 0xe3, v50
	v_bfe_u32 v54, v50, 2, 1
	v_lshl_or_b32 v53, v54, 4, v53
	v_bfe_u32 v54, v50, 3, 2
	v_lshl_or_b32 v53, v54, 2, v53
	v_lshlrev_b32_e32 v53, 11, v53
	v_lshl_add_u32 v53, v51, 4, v53
	v_cmp_lt_u32_e32 vcc, 0xff, v50
	v_cndmask_b32_e32 v52, v52, v53, vcc
	v_cmp_eq_u32_e32 vcc, 8, v51
	v_cndmask_b32_e64 v197, v52, 0, vcc
	v_add_u32_e32 v49, 0x800, v48
	v_mul_u32_u24_e32 v50, 0x1c72, v49
	v_lshrrev_b32_e32 v50, 16, v50
	v_mul_u32_u24_e32 v51, 9, v50
	v_sub_u32_e32 v51, v49, v51
	v_lshlrev_b32_e32 v52, 11, v50
	v_lshl_add_u32 v52, v51, 4, v52
	v_and_b32_e32 v53, 0xe3, v50
	v_bfe_u32 v54, v50, 2, 1
	v_lshl_or_b32 v53, v54, 4, v53
	v_bfe_u32 v54, v50, 3, 2
	v_lshl_or_b32 v53, v54, 2, v53
	v_lshlrev_b32_e32 v53, 11, v53
	v_lshl_add_u32 v53, v51, 4, v53
	v_cmp_lt_u32_e32 vcc, 0xff, v50
; template <int AMODE, int BN, class Epi>
; __device__ __forceinline__ void gemm_tile(const bf16_t* A, const int lda, const bf16_t* Bt, const int K, const int m0, const float* mu, char* lds, const Epi& epi) {
;     ...
;   f32x16 acc[MI][2];
; #pragma unroll
;   for (int i = 0; i < MI; ++i)
; #pragma unroll
;     for (int j = 0; j < 2; ++j)
; #pragma unroll
;       for (int r = 0; r < 16; ++r) acc[i][j][r] = 0.f;
;     ...
;   gload(0);
;   lstore(0, 0);
;   if (nk > 1) gload(64);
;   __syncthreads();
	v_cndmask_b32_e32 v52, v52, v53, vcc
	v_cmp_eq_u32_e32 vcc, 8, v51
	v_cndmask_b32_e64 v198, v52, 0, vcc
	v_add_u32_e32 v49, 0xa00, v48
	v_mul_u32_u24_e32 v50, 0x1c72, v49
	v_lshrrev_b32_e32 v50, 16, v50
	v_mul_u32_u24_e32 v51, 9, v50
	v_sub_u32_e32 v51, v49, v51
	v_lshlrev_b32_e32 v52, 11, v50
	v_lshl_add_u32 v52, v51, 4, v52
	v_and_b32_e32 v53, 0xe3, v50
	v_bfe_u32 v54, v50, 2, 1
	v_lshl_or_b32 v53, v54, 4, v53
	v_bfe_u32 v54, v50, 3, 2
	v_lshl_or_b32 v53, v54, 2, v53
	v_lshlrev_b32_e32 v53, 11, v53
	v_lshl_add_u32 v53, v51, 4, v53
	v_cmp_lt_u32_e32 vcc, 0xff, v50
	v_cndmask_b32_e32 v52, v52, v53, vcc
	v_cmp_eq_u32_e32 vcc, 8, v51
	v_cndmask_b32_e64 v199, v52, 0, vcc
	v_add_u32_e32 v49, 0xc00, v48
	v_mul_u32_u24_e32 v50, 0x1c72, v49
	v_lshrrev_b32_e32 v50, 16, v50
	v_mul_u32_u24_e32 v51, 9, v50
	v_sub_u32_e32 v51, v49, v51
	v_lshlrev_b32_e32 v52, 11, v50
	v_lshl_add_u32 v52, v51, 4, v52
	v_and_b32_e32 v53, 0xe3, v50
	v_bfe_u32 v54, v50, 2, 1
	v_lshl_or_b32 v53, v54, 4, v53
	v_bfe_u32 v54, v50, 3, 2
	v_lshl_or_b32 v53, v54, 2, v53
	v_lshlrev_b32_e32 v53, 11, v53
	v_lshl_add_u32 v53, v51, 4, v53
	v_cmp_lt_u32_e32 vcc, 0xff, v50
	v_cndmask_b32_e32 v52, v52, v53, vcc
	v_cmp_eq_u32_e32 vcc, 8, v51
	v_cndmask_b32_e64 v200, v52, 0, vcc
	v_add_u32_e32 v49, 0xe00, v48
	v_mul_u32_u24_e32 v50, 0x1c72, v49
	v_lshrrev_b32_e32 v50, 16, v50
	v_mul_u32_u24_e32 v51, 9, v50
	v_sub_u32_e32 v51, v49, v51
	v_lshlrev_b32_e32 v52, 11, v50
	v_lshl_add_u32 v52, v51, 4, v52
	v_and_b32_e32 v53, 0xe3, v50
	v_bfe_u32 v54, v50, 2, 1
	v_lshl_or_b32 v53, v54, 4, v53
	v_bfe_u32 v54, v50, 3, 2
	v_lshl_or_b32 v53, v54, 2, v53
	v_lshlrev_b32_e32 v53, 11, v53
	v_lshl_add_u32 v53, v51, 4, v53
	v_cmp_lt_u32_e32 vcc, 0xff, v50
	v_cndmask_b32_e32 v52, v52, v53, vcc
	v_cmp_eq_u32_e32 vcc, 8, v51
	v_cndmask_b32_e64 v201, v52, 0, vcc
	v_add_u32_e32 v49, 0x1000, v48
	v_mul_u32_u24_e32 v50, 0x1c72, v49
	v_lshrrev_b32_e32 v50, 16, v50
	v_mul_u32_u24_e32 v51, 9, v50
	v_sub_u32_e32 v51, v49, v51
	v_lshlrev_b32_e32 v52, 11, v50
	v_lshl_add_u32 v52, v51, 4, v52
	v_and_b32_e32 v53, 0xe3, v50
	v_bfe_u32 v54, v50, 2, 1
	v_lshl_or_b32 v53, v54, 4, v53
	v_bfe_u32 v54, v50, 3, 2
	v_lshl_or_b32 v53, v54, 2, v53
	v_lshlrev_b32_e32 v53, 11, v53
	v_lshl_add_u32 v53, v51, 4, v53
	v_cmp_lt_u32_e32 vcc, 0xff, v50
	v_cndmask_b32_e32 v52, v52, v53, vcc
	v_cmp_eq_u32_e32 vcc, 8, v51
	v_cndmask_b32_e64 v202, v52, 0, vcc
	v_mov_b32_e32 v48, v0
	v_mov_b32_e32 v49, v0
	v_mov_b32_e32 v50, v0
	v_mov_b32_e32 v51, v0
	v_mov_b32_e32 v52, v0
	v_mov_b32_e32 v53, v0
	v_mov_b32_e32 v54, v0
	v_mov_b32_e32 v55, v0
	v_mov_b32_e32 v56, v0
	v_mov_b32_e32 v57, v0
	v_mov_b32_e32 v58, v0
	v_mov_b32_e32 v59, v0
	v_mov_b32_e32 v60, v0
	v_mov_b32_e32 v61, v0
	v_mov_b32_e32 v62, v0
	v_mov_b32_e32 v63, v0
	v_mov_b32_e32 v64, v0
	v_mov_b32_e32 v65, v0
	s_waitcnt vmcnt(15)
	ds_write_b128 v185, v[16:19]
	s_waitcnt vmcnt(13)
	ds_write_b128 v185, v[20:23] offset:9216
	s_waitcnt vmcnt(12)
	ds_write_b128 v185, v[24:27] offset:18432
	s_waitcnt vmcnt(11)
	ds_write_b128 v185, v[28:31] offset:27648
	s_waitcnt vmcnt(10)
	ds_write_b128 v185, v[32:35] offset:36864
	s_waitcnt vmcnt(9)
	ds_write_b128 v185, v[36:39] offset:46080
	s_waitcnt vmcnt(8)
	ds_write_b128 v185, v[40:43] offset:55296
	s_waitcnt vmcnt(7)
	ds_write_b128 v185, v[44:47] offset:64512
	v_mov_b32_e32 v16, v0
	v_mov_b32_e32 v17, v0
	v_mov_b32_e32 v18, v0
	v_mov_b32_e32 v19, v0
	v_mov_b32_e32 v20, v0
	v_mov_b32_e32 v21, v0
	v_mov_b32_e32 v22, v0
	v_mov_b32_e32 v23, v0
	v_mov_b32_e32 v24, v0
	v_mov_b32_e32 v25, v0
	v_mov_b32_e32 v26, v0
	v_mov_b32_e32 v27, v0
	v_mov_b32_e32 v28, v0
	v_mov_b32_e32 v29, v0
	v_mov_b32_e32 v30, v0
	v_mov_b32_e32 v31, v0
	v_mov_b32_e32 v32, v0
	v_mov_b32_e32 v33, v0
	v_mov_b32_e32 v34, v0
	v_mov_b32_e32 v35, v0
	v_mov_b32_e32 v36, v0
	v_mov_b32_e32 v37, v0
	v_mov_b32_e32 v38, v0
	v_mov_b32_e32 v39, v0
	v_mov_b32_e32 v40, v0
	v_mov_b32_e32 v41, v0
	v_mov_b32_e32 v42, v0
	v_mov_b32_e32 v43, v0
	v_mov_b32_e32 v44, v0
	v_mov_b32_e32 v45, v0
	v_mov_b32_e32 v46, v0
	v_mov_b32_e32 v47, v0
	v_mov_b32_e32 v66, v0
	v_mov_b32_e32 v67, v0
	v_mov_b32_e32 v68, v0
	v_mov_b32_e32 v69, v0
	v_mov_b32_e32 v70, v0
	v_mov_b32_e32 v71, v0
	v_mov_b32_e32 v72, v0
	v_mov_b32_e32 v73, v0
	v_mov_b32_e32 v74, v0
	v_mov_b32_e32 v75, v0
	v_mov_b32_e32 v76, v0
	v_mov_b32_e32 v77, v0
	v_mov_b32_e32 v78, v0
	v_mov_b32_e32 v79, v0
	v_mov_b32_e32 v80, v0
	v_mov_b32_e32 v81, v0
	v_mov_b32_e32 v82, v0
	v_mov_b32_e32 v83, v0
	v_mov_b32_e32 v84, v0
	v_mov_b32_e32 v85, v0
	v_mov_b32_e32 v86, v0
	v_mov_b32_e32 v87, v0
	v_mov_b32_e32 v88, v0
	v_mov_b32_e32 v89, v0
	v_mov_b32_e32 v90, v0
	v_mov_b32_e32 v91, v0
	v_mov_b32_e32 v92, v0
	v_mov_b32_e32 v93, v0
	v_mov_b32_e32 v94, v0
	v_mov_b32_e32 v95, v0
	v_mov_b32_e32 v96, v0
	v_mov_b32_e32 v97, v0
	v_mov_b32_e32 v98, v0
	v_mov_b32_e32 v99, v0
	v_mov_b32_e32 v100, v0
	v_mov_b32_e32 v101, v0
	v_mov_b32_e32 v102, v0
	v_mov_b32_e32 v103, v0
	v_mov_b32_e32 v104, v0
	v_mov_b32_e32 v105, v0
	v_mov_b32_e32 v106, v0
	v_mov_b32_e32 v107, v0
	v_mov_b32_e32 v108, v0
	v_mov_b32_e32 v109, v0
	v_mov_b32_e32 v110, v0
	v_mov_b32_e32 v111, v0
	v_mov_b32_e32 v112, v0
	v_mov_b32_e32 v113, v0
	v_mov_b32_e32 v114, v0
	v_mov_b32_e32 v115, v0
	v_mov_b32_e32 v116, v0
	v_mov_b32_e32 v117, v0
	v_mov_b32_e32 v118, v0
	v_mov_b32_e32 v119, v0
	v_mov_b32_e32 v120, v0
	v_mov_b32_e32 v121, v0
	v_mov_b32_e32 v122, v0
	v_mov_b32_e32 v123, v0
	v_mov_b32_e32 v124, v0
	v_mov_b32_e32 v125, v0
	v_mov_b32_e32 v126, v0
	v_mov_b32_e32 v127, v0
	s_waitcnt lgkmcnt(0)
	s_barrier
	s_branch .LBB0_409
; #define MFMA(a, b, c) __builtin_amdgcn_mfma_f32_32x32x16_bf16((a), (b), (c), 0, 0, 0)
; template <int AMODE, int BN, class Epi>
; __device__ __forceinline__ void gemm_tile(const bf16_t* A, const int lda, const bf16_t* Bt, const int K, const int m0, const float* mu, char* lds, const Epi& epi) {
;     ...
; #pragma unroll 1
;   for (int kt = 0; kt < nk; ++kt) {
;     const int s = kt & 1;
;     if (kt + 1 < nk) lstore(s ^ 1, (kt + 1) * 64);
;     if (kt + 2 < nk) gload((kt + 2) * 64);
;     {
;       const char* Ab = lds + s * G_STAGE + (wm * (32 * MI) + r32) * G_LDT + hi * 16;
;       const char* Bb = lds + s * G_STAGE + 256 * G_LDT + (wn * 64 + r32) * G_LDT + hi * 16;
;       bf16x8 fb[2][2], fa[2][MI];
;       fb[0][0] = *(const bf16x8*)(Bb); fb[0][1] = *(const bf16x8*)(Bb + 32 * G_LDT);
; #pragma unroll
;       for (int mi = 0; mi < MI; ++mi) fa[0][mi] = *(const bf16x8*)(Ab + mi * 32 * G_LDT);
; #pragma unroll
;       for (int ks = 0; ks < 4; ++ks) {
;         const int sl = ks & 1;
;         if (ks + 1 < 4) {
;           fb[sl ^ 1][0] = *(const bf16x8*)(Bb + (ks + 1) * 32); fb[sl ^ 1][1] = *(const bf16x8*)(Bb + 32 * G_LDT + (ks + 1) * 32);
; #pragma unroll
;           for (int mi = 0; mi < MI; ++mi) fa[sl ^ 1][mi] = *(const bf16x8*)(Ab + mi * 32 * G_LDT + (ks + 1) * 32);
;         }
; #pragma unroll
;         for (int mi = 0; mi < MI; ++mi) { acc[mi][0] = MFMA(fb[sl][0], fa[sl][mi], acc[mi][0]); acc[mi][1] = MFMA(fb[sl][1], fa[sl][mi], acc[mi][1]); }
;       }
;     }
;     __syncthreads();
;   }
.LBB0_408:
	s_mul_i32 s18, s18, 0x12000
	s_add_i32 s18, s18, 0
	v_add3_u32 v173, s18, v205, v177
	ds_read_b128 v[212:215], v173 offset:36864
	v_add3_u32 v175, s18, v204, v177
	ds_read_b128 v[216:219], v175
	ds_read_b128 v[220:223], v173 offset:36896
	ds_read_b128 v[228:231], v175 offset:32
	ds_read_b128 v[232:235], v173 offset:41472
	ds_read_b128 v[236:239], v173 offset:41504
	s_waitcnt lgkmcnt(1)
	v_mfma_f32_32x32x16_bf16 v[96:111], v[232:235], v[216:219], v[96:111]
	s_add_u32 s16, s16, 0x80
	s_addc_u32 s17, s17, 0
	s_add_i32 s22, s22, 1
	s_cmpk_lg_i32 s16, 0x800
	v_mfma_f32_32x32x16_bf16 v[112:127], v[212:215], v[216:219], v[112:127]
	ds_read_b128 v[216:219], v175 offset:4608
	ds_read_b128 v[240:243], v175 offset:4640
	s_waitcnt lgkmcnt(1)
	v_mfma_f32_32x32x16_bf16 v[80:95], v[212:215], v[216:219], v[80:95]
	v_mfma_f32_32x32x16_bf16 v[64:79], v[232:235], v[216:219], v[64:79]
	ds_read_b128 v[216:219], v175 offset:9216
	ds_read_b128 v[244:247], v175 offset:9248
	s_waitcnt lgkmcnt(1)
	v_mfma_f32_32x32x16_bf16 v[48:63], v[212:215], v[216:219], v[48:63]
	v_mfma_f32_32x32x16_bf16 v[32:47], v[232:235], v[216:219], v[32:47]
	ds_read_b128 v[216:219], v175 offset:13824
	ds_read_b128 v[248:251], v175 offset:13856
	s_waitcnt lgkmcnt(1)
	v_mfma_f32_32x32x16_bf16 v[16:31], v[212:215], v[216:219], v[16:31]
	v_mfma_f32_32x32x16_bf16 v[0:15], v[232:235], v[216:219], v[0:15]
	v_mfma_f32_32x32x16_bf16 v[112:127], v[220:223], v[228:231], v[112:127]
	v_mfma_f32_32x32x16_bf16 v[96:111], v[236:239], v[228:231], v[96:111]
	v_mfma_f32_32x32x16_bf16 v[80:95], v[220:223], v[240:243], v[80:95]
	v_mfma_f32_32x32x16_bf16 v[64:79], v[236:239], v[240:243], v[64:79]
	v_mfma_f32_32x32x16_bf16 v[48:63], v[220:223], v[244:247], v[48:63]
	v_mfma_f32_32x32x16_bf16 v[32:47], v[236:239], v[244:247], v[32:47]
	s_waitcnt lgkmcnt(0)
	v_mfma_f32_32x32x16_bf16 v[16:31], v[220:223], v[248:251], v[16:31]
	ds_read_b128 v[212:215], v173 offset:36928
	ds_read_b128 v[216:219], v175 offset:64
	ds_read_b128 v[220:223], v173 offset:36960
	ds_read_b128 v[228:231], v175 offset:96
	v_mfma_f32_32x32x16_bf16 v[0:15], v[236:239], v[248:251], v[0:15]
	ds_read_b128 v[232:235], v173 offset:41536
	ds_read_b128 v[236:239], v173 offset:41568
	s_waitcnt lgkmcnt(4)
	v_mfma_f32_32x32x16_bf16 v[112:127], v[212:215], v[216:219], v[112:127]
	s_waitcnt lgkmcnt(1)
	v_mfma_f32_32x32x16_bf16 v[96:111], v[232:235], v[216:219], v[96:111]
	ds_read_b128 v[216:219], v175 offset:4672
	ds_read_b128 v[240:243], v175 offset:4704
	s_waitcnt lgkmcnt(1)
	v_mfma_f32_32x32x16_bf16 v[80:95], v[212:215], v[216:219], v[80:95]
	v_mfma_f32_32x32x16_bf16 v[64:79], v[232:235], v[216:219], v[64:79]
	ds_read_b128 v[216:219], v175 offset:9280
	ds_read_b128 v[244:247], v175 offset:9312
	s_waitcnt lgkmcnt(1)
	v_mfma_f32_32x32x16_bf16 v[48:63], v[212:215], v[216:219], v[48:63]
	v_mfma_f32_32x32x16_bf16 v[32:47], v[232:235], v[216:219], v[32:47]
	ds_read_b128 v[216:219], v175 offset:13888
	ds_read_b128 v[248:251], v175 offset:13920
	s_waitcnt vmcnt(0) lgkmcnt(0)
	s_barrier
	v_mfma_f32_32x32x16_bf16 v[16:31], v[212:215], v[216:219], v[16:31]
	v_mfma_f32_32x32x16_bf16 v[0:15], v[232:235], v[216:219], v[0:15]
	v_mfma_f32_32x32x16_bf16 v[112:127], v[220:223], v[228:231], v[112:127]
	v_mfma_f32_32x32x16_bf16 v[96:111], v[236:239], v[228:231], v[96:111]
	v_mfma_f32_32x32x16_bf16 v[80:95], v[220:223], v[240:243], v[80:95]
	v_mfma_f32_32x32x16_bf16 v[64:79], v[236:239], v[240:243], v[64:79]
	v_mfma_f32_32x32x16_bf16 v[48:63], v[220:223], v[244:247], v[48:63]
	v_mfma_f32_32x32x16_bf16 v[32:47], v[236:239], v[244:247], v[32:47]
	v_mfma_f32_32x32x16_bf16 v[16:31], v[220:223], v[248:251], v[16:31]
	v_mfma_f32_32x32x16_bf16 v[0:15], v[236:239], v[248:251], v[0:15]
	s_cbranch_scc0 .LBB0_394
.LBB0_409:
	s_and_b32 s18, s22, 1
	s_cmpk_eq_i32 s16, 0x780
	s_cbranch_scc1 .LBB0_411
	s_xor_b32 s19, s18, 1
	s_mul_i32 s19, s19, 0x12000
	s_add_i32 s97, s19, s96
	s_add_u32 s78, s66, s16
	s_addc_u32 s79, s67, s17
	s_add_u32 s90, s68, s16
	s_addc_u32 s91, s69, s17
	s_add_u32 s94, s72, s16
	s_addc_u32 s95, s73, s17
	s_add_i32 m0, s97, 0x0
	s_nop 0
	global_load_lds_dwordx4 v194, s[78:79]
	s_add_i32 m0, s97, 0x2000
	s_nop 0
	global_load_lds_dwordx4 v195, s[78:79]
	s_add_i32 m0, s97, 0x4000
	s_nop 0
	global_load_lds_dwordx4 v196, s[78:79]
	s_add_i32 m0, s97, 0x6000
	s_nop 0
	global_load_lds_dwordx4 v197, s[78:79]
	s_add_i32 m0, s97, 0x8000
	s_nop 0
	global_load_lds_dwordx4 v198, s[94:95]
	s_add_i32 m0, s97, 0xa000
	s_nop 0
	global_load_lds_dwordx4 v199, s[90:91]
	s_add_i32 m0, s97, 0xc000
	s_nop 0
	global_load_lds_dwordx4 v200, s[90:91]
	s_add_i32 m0, s97, 0xe000
	s_nop 0
	global_load_lds_dwordx4 v201, s[90:91]
	s_add_i32 m0, s97, 0x10000
	s_nop 0
	global_load_lds_dwordx4 v202, s[90:91]
.LBB0_411:
	s_branch .LBB0_408
.LBB0_413:
	s_lshl_b32 s4, s2, 1
	s_cmp_gt_u32 s4, s33
	s_cbranch_scc1 .LBB0_417
	v_readlane_b32 s5, v255, 12
	s_mov_b64 s[6:7], 0
	s_cmp_lt_u32 s5, s4
	s_mov_b64 s[4:5], 0
	s_cbranch_scc1 .LBB0_418
	s_and_b64 vcc, exec, s[6:7]
	s_cbranch_vccnz .LBB0_419
